# sample GEMM epilogues (mlpout A/B, oproj, glu): residual/bias loads issued at item start before the core instead of after the LDS reduction barrier
# speedup vs baseline: 1.0028x; 1.0028x over previous
.LBB0_369:
	s_and_b32 s14, s13, 0x60
	s_or_b32 s14, s14, s9
	v_and_or_b32 v168, s11, -16, v31
	v_ashrrev_i32_e32 v169, 31, v168
	v_lshlrev_b64 v[168:169], 2, v[168:169]
	v_lshl_add_u64 v[162:163], s[2:3], 0, v[168:169]
	global_load_dword v156, v[162:163], off
	s_mov_b32 s98, 0x1000
	s_mov_b32 s99, 0
	v_lshl_add_u64 v[162:163], v[162:163], 0, s[98:99]
	global_load_dword v157, v[162:163], off
	v_lshl_or_b32 v170, s14, 12, v32
	v_mov_b32_e32 v171, 0
	v_lshl_add_u64 v[164:165], s[0:1], 0, v[168:169]
	v_lshl_add_u64 v[164:165], v[164:165], 0, v[170:171]
	s_mov_b32 s98, 0x3000
	v_lshl_add_u64 v[166:167], v[164:165], 0, s[98:99]
	s_mov_b32 s98, 0x1000
	v_lshl_add_u64 v[164:165], v[164:165], 0, s[98:99]
	global_load_dword v158, v[164:165], off offset:-4096
	global_load_dword v159, v[164:165], off
	global_load_dword v160, v[166:167], off offset:-4096
	global_load_dword v161, v[166:167], off
	s_and_b32 s15, s12, 0xffffff00
	s_and_b32 s16, s11, 0x70
	s_or_b32 s22, s15, s16
	s_add_i32 s23, s22, 0x80
	v_readfirstlane_b32 s18, v26
	v_readfirstlane_b32 s19, v27
	v_readfirstlane_b32 s20, v28
	v_readfirstlane_b32 s21, v29
	v_and_b32_e32 v238, 63, v0
	v_lshrrev_b32_e32 v236, 2, v238
	v_and_b32_e32 v226, 3, v238
	v_add_u32_e32 v228, s22, v236
	v_lshlrev_b32_e32 v228, 11, v228
	v_lshl_add_u32 v228, v226, 4, v228
	v_add_u32_e32 v232, s23, v236
	v_lshlrev_b32_e32 v232, 11, v232
	v_lshl_add_u32 v232, v226, 4, v232
	v_add_u32_e32 v238, s14, v236
	v_lshlrev_b32_e32 v238, 12, v238
	v_lshl_add_u32 v226, v226, 5, v238
	v_and_b32_e32 v238, 63, v0
	v_and_b32_e32 v236, 15, v238
	v_lshrrev_b32_e32 v238, 4, v238
	v_lshl_add_u32 v236, v236, 2, v238
	v_lshlrev_b32_e32 v236, 2, v236
	v_mov_b32_e32 v14, 0
	global_load_dwordx4 v[16:19], v226, s[18:19]
	global_load_dwordx4 v[20:23], v226, s[18:19] offset:16
	global_load_dwordx4 v[34:37], v228, s[20:21]
	global_load_dwordx4 v[38:41], v232, s[20:21]
	global_load_dwordx4 v[42:45], v226, s[18:19] offset:128
	global_load_dwordx4 v[46:49], v226, s[18:19] offset:144
	global_load_dwordx4 v[50:53], v228, s[20:21] offset:64
	global_load_dwordx4 v[54:57], v232, s[20:21] offset:64
	global_load_dwordx4 v[58:61], v226, s[18:19] offset:256
	global_load_dwordx4 v[62:65], v226, s[18:19] offset:272
	global_load_dwordx4 v[66:69], v228, s[20:21] offset:128
	global_load_dwordx4 v[70:73], v232, s[20:21] offset:128
	global_load_dwordx4 v[74:77], v226, s[18:19] offset:384
	global_load_dwordx4 v[78:81], v226, s[18:19] offset:400
	global_load_dwordx4 v[82:85], v228, s[20:21] offset:192
	global_load_dwordx4 v[86:89], v232, s[20:21] offset:192
	global_load_dwordx4 v[90:93], v226, s[18:19] offset:512
	global_load_dwordx4 v[94:97], v226, s[18:19] offset:528
	global_load_dwordx4 v[98:101], v228, s[20:21] offset:256
	global_load_dwordx4 v[102:105], v232, s[20:21] offset:256
	global_load_dwordx4 v[106:109], v226, s[18:19] offset:640
	global_load_dwordx4 v[110:113], v226, s[18:19] offset:656
	global_load_dwordx4 v[114:117], v228, s[20:21] offset:320
	global_load_dwordx4 v[118:121], v232, s[20:21] offset:320
	global_load_dwordx4 v[122:125], v226, s[18:19] offset:768
	global_load_dwordx4 v[126:129], v226, s[18:19] offset:784
	global_load_dwordx4 v[130:133], v228, s[20:21] offset:384
	global_load_dwordx4 v[134:137], v232, s[20:21] offset:384
	global_load_dwordx4 v[138:141], v226, s[18:19] offset:896
	global_load_dwordx4 v[142:145], v226, s[18:19] offset:912
	global_load_dwordx4 v[146:149], v228, s[20:21] offset:448
	global_load_dwordx4 v[150:153], v232, s[20:21] offset:448
	s_waitcnt vmcnt(28)
	ds_bpermute_b32 v188, v236, v16
	ds_bpermute_b32 v189, v236, v17
	ds_bpermute_b32 v190, v236, v18
	ds_bpermute_b32 v191, v236, v19
	ds_bpermute_b32 v192, v236, v20
	ds_bpermute_b32 v193, v236, v21
	ds_bpermute_b32 v194, v236, v22
	ds_bpermute_b32 v195, v236, v23
	ds_bpermute_b32 v196, v236, v34
	ds_bpermute_b32 v197, v236, v35
	ds_bpermute_b32 v198, v236, v36
	ds_bpermute_b32 v199, v236, v37
	ds_bpermute_b32 v200, v236, v38
	ds_bpermute_b32 v201, v236, v39
	ds_bpermute_b32 v202, v236, v40
	ds_bpermute_b32 v203, v236, v41
	s_waitcnt lgkmcnt(8)
	v_fmac_f32_e32 v14, v188, v188
	v_fmac_f32_e32 v14, v189, v189
	v_fmac_f32_e32 v14, v190, v190
	v_fmac_f32_e32 v14, v191, v191
	v_fmac_f32_e32 v14, v192, v192
	v_fmac_f32_e32 v14, v193, v193
	v_fmac_f32_e32 v14, v194, v194
	v_fmac_f32_e32 v14, v195, v195
	v_cvt_pk_bf16_f32 v188, v188, v189
	v_cvt_pk_bf16_f32 v189, v190, v191
	v_cvt_pk_bf16_f32 v190, v192, v193
	v_cvt_pk_bf16_f32 v191, v194, v195
	s_waitcnt vmcnt(24)
	ds_bpermute_b32 v204, v236, v42
	ds_bpermute_b32 v205, v236, v43
	ds_bpermute_b32 v206, v236, v44
	ds_bpermute_b32 v207, v236, v45
	ds_bpermute_b32 v208, v236, v46
	ds_bpermute_b32 v209, v236, v47
	ds_bpermute_b32 v210, v236, v48
	ds_bpermute_b32 v211, v236, v49
	s_waitcnt lgkmcnt(12)
	v_mfma_f32_16x16x32_bf16 v[2:5], v[188:191], v[196:199], 0
	ds_bpermute_b32 v212, v236, v50
	ds_bpermute_b32 v213, v236, v51
	ds_bpermute_b32 v214, v236, v52
	ds_bpermute_b32 v215, v236, v53
	s_waitcnt lgkmcnt(12)
	v_mfma_f32_16x16x32_bf16 v[6:9], v[188:191], v[200:203], 0
	ds_bpermute_b32 v216, v236, v54
	ds_bpermute_b32 v217, v236, v55
	ds_bpermute_b32 v218, v236, v56
	ds_bpermute_b32 v219, v236, v57
	s_waitcnt lgkmcnt(8)
	v_fmac_f32_e32 v14, v204, v204
	v_fmac_f32_e32 v14, v205, v205
	v_fmac_f32_e32 v14, v206, v206
	v_fmac_f32_e32 v14, v207, v207
	v_fmac_f32_e32 v14, v208, v208
	v_fmac_f32_e32 v14, v209, v209
	v_fmac_f32_e32 v14, v210, v210
	v_fmac_f32_e32 v14, v211, v211
	v_cvt_pk_bf16_f32 v204, v204, v205
	v_cvt_pk_bf16_f32 v205, v206, v207
	v_cvt_pk_bf16_f32 v206, v208, v209
	v_cvt_pk_bf16_f32 v207, v210, v211
	s_waitcnt vmcnt(20)
	ds_bpermute_b32 v188, v236, v58
	ds_bpermute_b32 v189, v236, v59
	ds_bpermute_b32 v190, v236, v60
	ds_bpermute_b32 v191, v236, v61
	ds_bpermute_b32 v192, v236, v62
	ds_bpermute_b32 v193, v236, v63
	ds_bpermute_b32 v194, v236, v64
	ds_bpermute_b32 v195, v236, v65
	s_waitcnt lgkmcnt(12)
	v_mfma_f32_16x16x32_bf16 v[2:5], v[204:207], v[212:215], v[2:5]
	ds_bpermute_b32 v196, v236, v66
	ds_bpermute_b32 v197, v236, v67
	ds_bpermute_b32 v198, v236, v68
	ds_bpermute_b32 v199, v236, v69
	s_waitcnt lgkmcnt(12)
	v_mfma_f32_16x16x32_bf16 v[6:9], v[204:207], v[216:219], v[6:9]
	ds_bpermute_b32 v200, v236, v70
	ds_bpermute_b32 v201, v236, v71
	ds_bpermute_b32 v202, v236, v72
	ds_bpermute_b32 v203, v236, v73
	s_waitcnt lgkmcnt(8)
	v_fmac_f32_e32 v14, v188, v188
	v_fmac_f32_e32 v14, v189, v189
	v_fmac_f32_e32 v14, v190, v190
	v_fmac_f32_e32 v14, v191, v191
	v_fmac_f32_e32 v14, v192, v192
	v_fmac_f32_e32 v14, v193, v193
	v_fmac_f32_e32 v14, v194, v194
	v_fmac_f32_e32 v14, v195, v195
	v_cvt_pk_bf16_f32 v188, v188, v189
	v_cvt_pk_bf16_f32 v189, v190, v191
	v_cvt_pk_bf16_f32 v190, v192, v193
	v_cvt_pk_bf16_f32 v191, v194, v195
	s_waitcnt vmcnt(16)
	ds_bpermute_b32 v204, v236, v74
	ds_bpermute_b32 v205, v236, v75
	ds_bpermute_b32 v206, v236, v76
	ds_bpermute_b32 v207, v236, v77
	ds_bpermute_b32 v208, v236, v78
	ds_bpermute_b32 v209, v236, v79
	ds_bpermute_b32 v210, v236, v80
	ds_bpermute_b32 v211, v236, v81
	s_waitcnt lgkmcnt(12)
	v_mfma_f32_16x16x32_bf16 v[2:5], v[188:191], v[196:199], v[2:5]
	ds_bpermute_b32 v212, v236, v82
	ds_bpermute_b32 v213, v236, v83
	ds_bpermute_b32 v214, v236, v84
	ds_bpermute_b32 v215, v236, v85
	s_waitcnt lgkmcnt(12)
	v_mfma_f32_16x16x32_bf16 v[6:9], v[188:191], v[200:203], v[6:9]
	ds_bpermute_b32 v216, v236, v86
	ds_bpermute_b32 v217, v236, v87
	ds_bpermute_b32 v218, v236, v88
	ds_bpermute_b32 v219, v236, v89
	s_waitcnt lgkmcnt(8)
	v_fmac_f32_e32 v14, v204, v204
	v_fmac_f32_e32 v14, v205, v205
	v_fmac_f32_e32 v14, v206, v206
	v_fmac_f32_e32 v14, v207, v207
	v_fmac_f32_e32 v14, v208, v208
	v_fmac_f32_e32 v14, v209, v209
	v_fmac_f32_e32 v14, v210, v210
	v_fmac_f32_e32 v14, v211, v211
	v_cvt_pk_bf16_f32 v204, v204, v205
	v_cvt_pk_bf16_f32 v205, v206, v207
	v_cvt_pk_bf16_f32 v206, v208, v209
	v_cvt_pk_bf16_f32 v207, v210, v211
	s_waitcnt vmcnt(12)
	ds_bpermute_b32 v188, v236, v90
	ds_bpermute_b32 v189, v236, v91
	ds_bpermute_b32 v190, v236, v92
	ds_bpermute_b32 v191, v236, v93
	ds_bpermute_b32 v192, v236, v94
	ds_bpermute_b32 v193, v236, v95
	ds_bpermute_b32 v194, v236, v96
	ds_bpermute_b32 v195, v236, v97
	s_waitcnt lgkmcnt(12)
	v_mfma_f32_16x16x32_bf16 v[2:5], v[204:207], v[212:215], v[2:5]
	ds_bpermute_b32 v196, v236, v98
	ds_bpermute_b32 v197, v236, v99
	ds_bpermute_b32 v198, v236, v100
	ds_bpermute_b32 v199, v236, v101
	s_waitcnt lgkmcnt(12)
	v_mfma_f32_16x16x32_bf16 v[6:9], v[204:207], v[216:219], v[6:9]
	ds_bpermute_b32 v200, v236, v102
	ds_bpermute_b32 v201, v236, v103
	ds_bpermute_b32 v202, v236, v104
	ds_bpermute_b32 v203, v236, v105
	s_waitcnt lgkmcnt(8)
	v_fmac_f32_e32 v14, v188, v188
	v_fmac_f32_e32 v14, v189, v189
	v_fmac_f32_e32 v14, v190, v190
	v_fmac_f32_e32 v14, v191, v191
	v_fmac_f32_e32 v14, v192, v192
	v_fmac_f32_e32 v14, v193, v193
	v_fmac_f32_e32 v14, v194, v194
	v_fmac_f32_e32 v14, v195, v195
	v_cvt_pk_bf16_f32 v188, v188, v189
	v_cvt_pk_bf16_f32 v189, v190, v191
	v_cvt_pk_bf16_f32 v190, v192, v193
	v_cvt_pk_bf16_f32 v191, v194, v195
	s_waitcnt vmcnt(8)
	ds_bpermute_b32 v204, v236, v106
	ds_bpermute_b32 v205, v236, v107
	ds_bpermute_b32 v206, v236, v108
	ds_bpermute_b32 v207, v236, v109
	ds_bpermute_b32 v208, v236, v110
	ds_bpermute_b32 v209, v236, v111
	ds_bpermute_b32 v210, v236, v112
	ds_bpermute_b32 v211, v236, v113
	s_waitcnt lgkmcnt(12)
	v_mfma_f32_16x16x32_bf16 v[2:5], v[188:191], v[196:199], v[2:5]
	ds_bpermute_b32 v212, v236, v114
	ds_bpermute_b32 v213, v236, v115
	ds_bpermute_b32 v214, v236, v116
	ds_bpermute_b32 v215, v236, v117
	s_waitcnt lgkmcnt(12)
	v_mfma_f32_16x16x32_bf16 v[6:9], v[188:191], v[200:203], v[6:9]
	ds_bpermute_b32 v216, v236, v118
	ds_bpermute_b32 v217, v236, v119
	ds_bpermute_b32 v218, v236, v120
	ds_bpermute_b32 v219, v236, v121
	s_waitcnt lgkmcnt(8)
	v_fmac_f32_e32 v14, v204, v204
	v_fmac_f32_e32 v14, v205, v205
	v_fmac_f32_e32 v14, v206, v206
	v_fmac_f32_e32 v14, v207, v207
	v_fmac_f32_e32 v14, v208, v208
	v_fmac_f32_e32 v14, v209, v209
	v_fmac_f32_e32 v14, v210, v210
	v_fmac_f32_e32 v14, v211, v211
	v_cvt_pk_bf16_f32 v204, v204, v205
	v_cvt_pk_bf16_f32 v205, v206, v207
	v_cvt_pk_bf16_f32 v206, v208, v209
	v_cvt_pk_bf16_f32 v207, v210, v211
	s_waitcnt vmcnt(4)
	ds_bpermute_b32 v188, v236, v122
	ds_bpermute_b32 v189, v236, v123
	ds_bpermute_b32 v190, v236, v124
	ds_bpermute_b32 v191, v236, v125
	ds_bpermute_b32 v192, v236, v126
	ds_bpermute_b32 v193, v236, v127
	ds_bpermute_b32 v194, v236, v128
	ds_bpermute_b32 v195, v236, v129
	s_waitcnt lgkmcnt(12)
	v_mfma_f32_16x16x32_bf16 v[2:5], v[204:207], v[212:215], v[2:5]
	ds_bpermute_b32 v196, v236, v130
	ds_bpermute_b32 v197, v236, v131
	ds_bpermute_b32 v198, v236, v132
	ds_bpermute_b32 v199, v236, v133
	s_waitcnt lgkmcnt(12)
	v_mfma_f32_16x16x32_bf16 v[6:9], v[204:207], v[216:219], v[6:9]
	ds_bpermute_b32 v200, v236, v134
	ds_bpermute_b32 v201, v236, v135
	ds_bpermute_b32 v202, v236, v136
	ds_bpermute_b32 v203, v236, v137
	s_waitcnt lgkmcnt(8)
	v_fmac_f32_e32 v14, v188, v188
	v_fmac_f32_e32 v14, v189, v189
	v_fmac_f32_e32 v14, v190, v190
	v_fmac_f32_e32 v14, v191, v191
	v_fmac_f32_e32 v14, v192, v192
	v_fmac_f32_e32 v14, v193, v193
	v_fmac_f32_e32 v14, v194, v194
	v_fmac_f32_e32 v14, v195, v195
	v_cvt_pk_bf16_f32 v188, v188, v189
	v_cvt_pk_bf16_f32 v189, v190, v191
	v_cvt_pk_bf16_f32 v190, v192, v193
	v_cvt_pk_bf16_f32 v191, v194, v195
	s_waitcnt vmcnt(0)
	ds_bpermute_b32 v204, v236, v138
	ds_bpermute_b32 v205, v236, v139
	ds_bpermute_b32 v206, v236, v140
	ds_bpermute_b32 v207, v236, v141
	ds_bpermute_b32 v208, v236, v142
	ds_bpermute_b32 v209, v236, v143
	ds_bpermute_b32 v210, v236, v144
	ds_bpermute_b32 v211, v236, v145
	s_waitcnt lgkmcnt(12)
	v_mfma_f32_16x16x32_bf16 v[2:5], v[188:191], v[196:199], v[2:5]
	ds_bpermute_b32 v212, v236, v146
	ds_bpermute_b32 v213, v236, v147
	ds_bpermute_b32 v214, v236, v148
	ds_bpermute_b32 v215, v236, v149
	s_waitcnt lgkmcnt(12)
	v_mfma_f32_16x16x32_bf16 v[6:9], v[188:191], v[200:203], v[6:9]
	ds_bpermute_b32 v216, v236, v150
	ds_bpermute_b32 v217, v236, v151
	ds_bpermute_b32 v218, v236, v152
	ds_bpermute_b32 v219, v236, v153
	s_waitcnt lgkmcnt(8)
	v_fmac_f32_e32 v14, v204, v204
	v_fmac_f32_e32 v14, v205, v205
	v_fmac_f32_e32 v14, v206, v206
	v_fmac_f32_e32 v14, v207, v207
	v_fmac_f32_e32 v14, v208, v208
	v_fmac_f32_e32 v14, v209, v209
	v_fmac_f32_e32 v14, v210, v210
	v_fmac_f32_e32 v14, v211, v211
	v_cvt_pk_bf16_f32 v204, v204, v205
	v_cvt_pk_bf16_f32 v205, v206, v207
	v_cvt_pk_bf16_f32 v206, v208, v209
	v_cvt_pk_bf16_f32 v207, v210, v211
	s_nop 1
	s_waitcnt lgkmcnt(4)
	v_mfma_f32_16x16x32_bf16 v[2:5], v[204:207], v[212:215], v[2:5]
	s_waitcnt lgkmcnt(0)
	v_mfma_f32_16x16x32_bf16 v[6:9], v[204:207], v[216:219], v[6:9]
	v_and_b32_e32 v240, 63, v0
	v_xor_b32_e32 v242, 32, v240
	v_xor_b32_e32 v240, 16, v240
	v_lshlrev_b32_e32 v240, 2, v240
	v_lshlrev_b32_e32 v242, 2, v242
	ds_bpermute_b32 v238, v240, v14
	s_waitcnt lgkmcnt(0)
	v_add_f32_e32 v14, v14, v238
	ds_bpermute_b32 v238, v242, v14
	s_waitcnt lgkmcnt(0)
	v_add_f32_e32 v14, v14, v238
	v_mov_b32_e32 v15, 0
	s_barrier
	s_nop 7
	ds_write_b128 v33, v[2:5]
	s_nop 1
	ds_write_b128 v33, v[6:9] offset:1024
	v_add_u32_e32 v2, s10, v30
	v_add_f32_e32 v10, v14, v15
	s_andn2_b64 vcc, exec, s[4:5]
	ds_write_b32 v2, v10 offset:32768
	s_waitcnt lgkmcnt(0)
	s_barrier
	s_cbranch_vccnz .LBB0_368
	v_and_or_b32 v2, s11, -16, v31
	v_ashrrev_i32_e32 v3, 31, v2
	v_lshlrev_b64 v[2:3], 2, v[2:3]
	v_lshl_add_u64 v[4:5], s[2:3], 0, v[2:3]
	v_add_co_u32_e32 v4, vcc, 0x1000, v4
	v_lshl_or_b32 v154, s14, 12, v32
	s_nop 0
	v_addc_co_u32_e32 v5, vcc, 0, v5, vcc
	v_lshl_add_u64 v[2:3], s[0:1], 0, v[2:3]
	v_lshl_add_u64 v[42:43], v[2:3], 0, v[154:155]
	v_add_co_u32_e32 v44, vcc, s96, v42
	s_nop 1
	v_addc_co_u32_e32 v45, vcc, 0, v43, vcc
	v_add_co_u32_e32 v46, vcc, 0x3000, v42
	s_nop 1
	v_addc_co_u32_e32 v47, vcc, 0, v43, vcc
	ds_read_b128 v[2:5], v33 offset:12288
	ds_read_b128 v[6:9], v33
	ds_read_b128 v[10:13], v33 offset:1024
	ds_read_b128 v[14:17], v33 offset:4096
	ds_read_b128 v[18:21], v33 offset:5120
	ds_read_b128 v[22:25], v33 offset:8192
	ds_read_b128 v[34:37], v33 offset:9216
	ds_read_b128 v[38:41], v33 offset:13312
	s_waitcnt lgkmcnt(4)
	v_add_f32_e32 v6, v6, v14
	s_waitcnt lgkmcnt(3)
	v_add_f32_e32 v10, v10, v18
	s_waitcnt lgkmcnt(2)
	v_add_f32_e32 v2, v22, v2
	v_add_f32_e32 v7, v7, v15
	s_waitcnt lgkmcnt(0)
	v_add_f32_e32 v14, v34, v38
	v_add_f32_e32 v3, v23, v3
	v_add_f32_e32 v11, v11, v19
	v_add_f32_e32 v15, v35, v39
	v_add_f32_e32 v8, v8, v16
	v_add_f32_e32 v4, v24, v4
	v_add_f32_e32 v12, v12, v20
	v_add_f32_e32 v16, v36, v40
	v_add_f32_e32 v9, v9, v17
	v_add_f32_e32 v5, v25, v5
	v_add_f32_e32 v13, v13, v21
	v_add_f32_e32 v17, v37, v41
	v_add_f32_e32 v2, v6, v2
	v_add_f32_e32 v6, v10, v14
	v_add_f32_e32 v3, v7, v3
	v_add_f32_e32 v7, v11, v15
	v_add_f32_e32 v4, v8, v4
	v_add_f32_e32 v8, v12, v16
	v_add_f32_e32 v5, v9, v5
	v_add_f32_e32 v9, v13, v17
	s_waitcnt vmcnt(5)
	v_add_f32_e32 v2, v2, v156
	v_add_f32_e32 v3, v3, v156
	v_add_f32_e32 v4, v4, v156
	v_add_f32_e32 v5, v5, v156
	s_waitcnt vmcnt(4)
	v_add_f32_e32 v6, v157, v6
	v_add_f32_e32 v7, v157, v7
	v_add_f32_e32 v8, v157, v8
	v_add_f32_e32 v9, v157, v9
	v_mul_f32_e32 v6, 0xbfb8aa3b, v6
	v_mul_f32_e32 v7, 0xbfb8aa3b, v7
	v_mul_f32_e32 v8, 0xbfb8aa3b, v8
	v_mul_f32_e32 v9, 0xbfb8aa3b, v9
	v_exp_f32_e32 v6, v6
	v_exp_f32_e32 v7, v7
	v_exp_f32_e32 v8, v8
	v_exp_f32_e32 v9, v9
	v_add_f32_e32 v6, 1.0, v6
	v_add_f32_e32 v7, 1.0, v7
	v_add_f32_e32 v8, 1.0, v8
	v_add_f32_e32 v9, 1.0, v9
	v_rcp_f32_e32 v6, v6
	v_rcp_f32_e32 v7, v7
	v_rcp_f32_e32 v8, v8
	v_rcp_f32_e32 v9, v9
	s_waitcnt vmcnt(3)
	v_fmac_f32_e32 v158, v2, v6
	s_waitcnt vmcnt(2)
	v_fmac_f32_e32 v159, v3, v7
	s_waitcnt vmcnt(1)
	v_fmac_f32_e32 v160, v4, v8
	s_waitcnt vmcnt(0)
	v_fmac_f32_e32 v161, v5, v9
	global_store_dword v[42:43], v158, off
	global_store_dword v[44:45], v159, off offset:-4096
	global_store_dword v[44:45], v160, off
	global_store_dword v[46:47], v161, off
	s_branch .LBB0_368

.LBB0_559:
	s_and_b32 s4, s10, 0x60
	s_or_b32 s11, s4, s7
	s_and_b32 s98, s9, -16
	s_ashr_i32 s99, s98, 31
	v_lshl_or_b32 v154, s11, 12, v10
	v_lshl_add_u64 v[248:249], s[98:99], 2, v[6:7]
	v_lshl_add_u64 v[248:249], v[248:249], 0, v[154:155]
	s_mov_b32 s98, 0x3000
	s_mov_b32 s99, 0
	v_lshl_add_u64 v[250:251], v[248:249], 0, s[98:99]
	s_mov_b32 s98, 0x1000
	v_lshl_add_u64 v[248:249], v[248:249], 0, s[98:99]
	global_load_dword v234, v[248:249], off offset:-4096
	global_load_dword v236, v[248:249], off
	global_load_dword v238, v[250:251], off offset:-4096
	global_load_dword v240, v[250:251], off
	v_readfirstlane_b32 s12, v4
	v_readfirstlane_b32 s13, v5
	v_readfirstlane_b32 s14, v2
	v_readfirstlane_b32 s15, v3
	s_and_b32 s16, s9, -16
	v_and_b32_e32 v233, 63, v0
	v_lshrrev_b32_e32 v232, 2, v233
	v_and_b32_e32 v226, 3, v233
	v_lshlrev_b32_e32 v226, 4, v226
	v_add_u32_e32 v228, s16, v232
	v_lshl_add_u32 v228, v228, 13, v226
	v_add_u32_e32 v233, s11, v232
	v_lshl_add_u32 v226, v233, 13, v226
	v_and_b32_e32 v233, 63, v0
	v_and_b32_e32 v232, 15, v233
	v_lshrrev_b32_e32 v233, 4, v233
	v_lshl_add_u32 v232, v232, 2, v233
	v_lshlrev_b32_e32 v232, 2, v232
	global_load_dwordx4 v[16:19], v226, s[12:13]
	global_load_dwordx4 v[20:23], v228, s[14:15]
	global_load_dwordx4 v[24:27], v226, s[12:13] offset:64
	global_load_dwordx4 v[28:31], v228, s[14:15] offset:64
	global_load_dwordx4 v[32:35], v226, s[12:13] offset:128
	global_load_dwordx4 v[36:39], v228, s[14:15] offset:128
	global_load_dwordx4 v[40:43], v226, s[12:13] offset:192
	global_load_dwordx4 v[44:47], v228, s[14:15] offset:192
	global_load_dwordx4 v[48:51], v226, s[12:13] offset:256
	global_load_dwordx4 v[52:55], v228, s[14:15] offset:256
	global_load_dwordx4 v[56:59], v226, s[12:13] offset:320
	global_load_dwordx4 v[60:63], v228, s[14:15] offset:320
	global_load_dwordx4 v[64:67], v226, s[12:13] offset:384
	global_load_dwordx4 v[68:71], v228, s[14:15] offset:384
	global_load_dwordx4 v[72:75], v226, s[12:13] offset:448
	global_load_dwordx4 v[76:79], v228, s[14:15] offset:448
	global_load_dwordx4 v[80:83], v226, s[12:13] offset:512
	global_load_dwordx4 v[84:87], v228, s[14:15] offset:512
	global_load_dwordx4 v[88:91], v226, s[12:13] offset:576
	global_load_dwordx4 v[92:95], v228, s[14:15] offset:576
	global_load_dwordx4 v[96:99], v226, s[12:13] offset:640
	global_load_dwordx4 v[100:103], v228, s[14:15] offset:640
	global_load_dwordx4 v[104:107], v226, s[12:13] offset:704
	global_load_dwordx4 v[108:111], v228, s[14:15] offset:704
	global_load_dwordx4 v[112:115], v226, s[12:13] offset:768
	global_load_dwordx4 v[116:119], v228, s[14:15] offset:768
	global_load_dwordx4 v[120:123], v226, s[12:13] offset:832
	global_load_dwordx4 v[124:127], v228, s[14:15] offset:832
	global_load_dwordx4 v[128:131], v226, s[12:13] offset:896
	global_load_dwordx4 v[132:135], v228, s[14:15] offset:896
	global_load_dwordx4 v[136:139], v226, s[12:13] offset:960
	global_load_dwordx4 v[140:143], v228, s[14:15] offset:960
	global_load_dwordx4 v[144:147], v226, s[12:13] offset:1024
	global_load_dwordx4 v[148:151], v228, s[14:15] offset:1024
	global_load_dwordx4 v[156:159], v226, s[12:13] offset:1088
	global_load_dwordx4 v[160:163], v228, s[14:15] offset:1088
	global_load_dwordx4 v[164:167], v226, s[12:13] offset:1152
	global_load_dwordx4 v[168:171], v228, s[14:15] offset:1152
	global_load_dwordx4 v[172:175], v226, s[12:13] offset:1216
	global_load_dwordx4 v[176:179], v228, s[14:15] offset:1216
	s_waitcnt vmcnt(38)
	ds_bpermute_b32 v196, v232, v16
	ds_bpermute_b32 v197, v232, v17
	ds_bpermute_b32 v198, v232, v18
	ds_bpermute_b32 v199, v232, v19
	ds_bpermute_b32 v200, v232, v20
	ds_bpermute_b32 v201, v232, v21
	ds_bpermute_b32 v202, v232, v22
	ds_bpermute_b32 v203, v232, v23
	global_load_dwordx4 v[16:19], v226, s[12:13] offset:1280
	global_load_dwordx4 v[20:23], v228, s[14:15] offset:1280
	s_waitcnt vmcnt(38)
	ds_bpermute_b32 v204, v232, v24
	ds_bpermute_b32 v205, v232, v25
	ds_bpermute_b32 v206, v232, v26
	ds_bpermute_b32 v207, v232, v27
	s_waitcnt lgkmcnt(4)
	v_mfma_f32_16x16x32_bf16 v[12:15], v[196:199], v[200:203], 0
	ds_bpermute_b32 v208, v232, v28
	ds_bpermute_b32 v209, v232, v29
	ds_bpermute_b32 v210, v232, v30
	ds_bpermute_b32 v211, v232, v31
	global_load_dwordx4 v[24:27], v226, s[12:13] offset:1344
	global_load_dwordx4 v[28:31], v228, s[14:15] offset:1344
	s_waitcnt vmcnt(38)
	ds_bpermute_b32 v212, v232, v32
	ds_bpermute_b32 v213, v232, v33
	ds_bpermute_b32 v214, v232, v34
	ds_bpermute_b32 v215, v232, v35
	s_waitcnt lgkmcnt(4)
	v_mfma_f32_16x16x32_bf16 v[12:15], v[204:207], v[208:211], v[12:15]
	ds_bpermute_b32 v216, v232, v36
	ds_bpermute_b32 v217, v232, v37
	ds_bpermute_b32 v218, v232, v38
	ds_bpermute_b32 v219, v232, v39
	global_load_dwordx4 v[32:35], v226, s[12:13] offset:1408
	global_load_dwordx4 v[36:39], v228, s[14:15] offset:1408
	s_waitcnt vmcnt(38)
	ds_bpermute_b32 v196, v232, v40
	ds_bpermute_b32 v197, v232, v41
	ds_bpermute_b32 v198, v232, v42
	ds_bpermute_b32 v199, v232, v43
	s_waitcnt lgkmcnt(4)
	v_mfma_f32_16x16x32_bf16 v[12:15], v[212:215], v[216:219], v[12:15]
	ds_bpermute_b32 v200, v232, v44
	ds_bpermute_b32 v201, v232, v45
	ds_bpermute_b32 v202, v232, v46
	ds_bpermute_b32 v203, v232, v47
	global_load_dwordx4 v[40:43], v226, s[12:13] offset:1472
	global_load_dwordx4 v[44:47], v228, s[14:15] offset:1472
	s_waitcnt vmcnt(38)
	ds_bpermute_b32 v204, v232, v48
	ds_bpermute_b32 v205, v232, v49
	ds_bpermute_b32 v206, v232, v50
	ds_bpermute_b32 v207, v232, v51
	s_waitcnt lgkmcnt(4)
	v_mfma_f32_16x16x32_bf16 v[12:15], v[196:199], v[200:203], v[12:15]
	ds_bpermute_b32 v208, v232, v52
	ds_bpermute_b32 v209, v232, v53
	ds_bpermute_b32 v210, v232, v54
	ds_bpermute_b32 v211, v232, v55
	global_load_dwordx4 v[48:51], v226, s[12:13] offset:1536
	global_load_dwordx4 v[52:55], v228, s[14:15] offset:1536
	s_waitcnt vmcnt(38)
	ds_bpermute_b32 v212, v232, v56
	ds_bpermute_b32 v213, v232, v57
	ds_bpermute_b32 v214, v232, v58
	ds_bpermute_b32 v215, v232, v59
	s_waitcnt lgkmcnt(4)
	v_mfma_f32_16x16x32_bf16 v[12:15], v[204:207], v[208:211], v[12:15]
	ds_bpermute_b32 v216, v232, v60
	ds_bpermute_b32 v217, v232, v61
	ds_bpermute_b32 v218, v232, v62
	ds_bpermute_b32 v219, v232, v63
	global_load_dwordx4 v[56:59], v226, s[12:13] offset:1600
	global_load_dwordx4 v[60:63], v228, s[14:15] offset:1600
	s_waitcnt vmcnt(38)
	ds_bpermute_b32 v196, v232, v64
	ds_bpermute_b32 v197, v232, v65
	ds_bpermute_b32 v198, v232, v66
	ds_bpermute_b32 v199, v232, v67
	s_waitcnt lgkmcnt(4)
	v_mfma_f32_16x16x32_bf16 v[12:15], v[212:215], v[216:219], v[12:15]
	ds_bpermute_b32 v200, v232, v68
	ds_bpermute_b32 v201, v232, v69
	ds_bpermute_b32 v202, v232, v70
	ds_bpermute_b32 v203, v232, v71
	global_load_dwordx4 v[64:67], v226, s[12:13] offset:1664
	global_load_dwordx4 v[68:71], v228, s[14:15] offset:1664
	s_waitcnt vmcnt(38)
	ds_bpermute_b32 v204, v232, v72
	ds_bpermute_b32 v205, v232, v73
	ds_bpermute_b32 v206, v232, v74
	ds_bpermute_b32 v207, v232, v75
	s_waitcnt lgkmcnt(4)
	v_mfma_f32_16x16x32_bf16 v[12:15], v[196:199], v[200:203], v[12:15]
	ds_bpermute_b32 v208, v232, v76
	ds_bpermute_b32 v209, v232, v77
	ds_bpermute_b32 v210, v232, v78
	ds_bpermute_b32 v211, v232, v79
	global_load_dwordx4 v[72:75], v226, s[12:13] offset:1728
	global_load_dwordx4 v[76:79], v228, s[14:15] offset:1728
	s_waitcnt vmcnt(38)
	ds_bpermute_b32 v212, v232, v80
	ds_bpermute_b32 v213, v232, v81
	ds_bpermute_b32 v214, v232, v82
	ds_bpermute_b32 v215, v232, v83
	s_waitcnt lgkmcnt(4)
	v_mfma_f32_16x16x32_bf16 v[12:15], v[204:207], v[208:211], v[12:15]
	ds_bpermute_b32 v216, v232, v84
	ds_bpermute_b32 v217, v232, v85
	ds_bpermute_b32 v218, v232, v86
	ds_bpermute_b32 v219, v232, v87
	global_load_dwordx4 v[80:83], v226, s[12:13] offset:1792
	global_load_dwordx4 v[84:87], v228, s[14:15] offset:1792
	s_waitcnt vmcnt(38)
	ds_bpermute_b32 v196, v232, v88
	ds_bpermute_b32 v197, v232, v89
	ds_bpermute_b32 v198, v232, v90
	ds_bpermute_b32 v199, v232, v91
	s_waitcnt lgkmcnt(4)
	v_mfma_f32_16x16x32_bf16 v[12:15], v[212:215], v[216:219], v[12:15]
	ds_bpermute_b32 v200, v232, v92
	ds_bpermute_b32 v201, v232, v93
	ds_bpermute_b32 v202, v232, v94
	ds_bpermute_b32 v203, v232, v95
	global_load_dwordx4 v[88:91], v226, s[12:13] offset:1856
	global_load_dwordx4 v[92:95], v228, s[14:15] offset:1856
	s_waitcnt vmcnt(38)
	ds_bpermute_b32 v204, v232, v96
	ds_bpermute_b32 v205, v232, v97
	ds_bpermute_b32 v206, v232, v98
	ds_bpermute_b32 v207, v232, v99
	s_waitcnt lgkmcnt(4)
	v_mfma_f32_16x16x32_bf16 v[12:15], v[196:199], v[200:203], v[12:15]
	ds_bpermute_b32 v208, v232, v100
	ds_bpermute_b32 v209, v232, v101
	ds_bpermute_b32 v210, v232, v102
	ds_bpermute_b32 v211, v232, v103
	global_load_dwordx4 v[96:99], v226, s[12:13] offset:1920
	global_load_dwordx4 v[100:103], v228, s[14:15] offset:1920
	s_waitcnt vmcnt(38)
	ds_bpermute_b32 v212, v232, v104
	ds_bpermute_b32 v213, v232, v105
	ds_bpermute_b32 v214, v232, v106
	ds_bpermute_b32 v215, v232, v107
	s_waitcnt lgkmcnt(4)
	v_mfma_f32_16x16x32_bf16 v[12:15], v[204:207], v[208:211], v[12:15]
	ds_bpermute_b32 v216, v232, v108
	ds_bpermute_b32 v217, v232, v109
	ds_bpermute_b32 v218, v232, v110
	ds_bpermute_b32 v219, v232, v111
	global_load_dwordx4 v[104:107], v226, s[12:13] offset:1984
	global_load_dwordx4 v[108:111], v228, s[14:15] offset:1984
	s_waitcnt vmcnt(38)
	ds_bpermute_b32 v196, v232, v112
	ds_bpermute_b32 v197, v232, v113
	ds_bpermute_b32 v198, v232, v114
	ds_bpermute_b32 v199, v232, v115
	s_waitcnt lgkmcnt(4)
	v_mfma_f32_16x16x32_bf16 v[12:15], v[212:215], v[216:219], v[12:15]
	ds_bpermute_b32 v200, v232, v116
	ds_bpermute_b32 v201, v232, v117
	ds_bpermute_b32 v202, v232, v118
	ds_bpermute_b32 v203, v232, v119
	s_waitcnt vmcnt(36)
	ds_bpermute_b32 v204, v232, v120
	ds_bpermute_b32 v205, v232, v121
	ds_bpermute_b32 v206, v232, v122
	ds_bpermute_b32 v207, v232, v123
	s_waitcnt lgkmcnt(4)
	v_mfma_f32_16x16x32_bf16 v[12:15], v[196:199], v[200:203], v[12:15]
	ds_bpermute_b32 v208, v232, v124
	ds_bpermute_b32 v209, v232, v125
	ds_bpermute_b32 v210, v232, v126
	ds_bpermute_b32 v211, v232, v127
	s_waitcnt vmcnt(34)
	ds_bpermute_b32 v212, v232, v128
	ds_bpermute_b32 v213, v232, v129
	ds_bpermute_b32 v214, v232, v130
	ds_bpermute_b32 v215, v232, v131
	s_waitcnt lgkmcnt(4)
	v_mfma_f32_16x16x32_bf16 v[12:15], v[204:207], v[208:211], v[12:15]
	ds_bpermute_b32 v216, v232, v132
	ds_bpermute_b32 v217, v232, v133
	ds_bpermute_b32 v218, v232, v134
	ds_bpermute_b32 v219, v232, v135
	s_waitcnt vmcnt(32)
	ds_bpermute_b32 v196, v232, v136
	ds_bpermute_b32 v197, v232, v137
	ds_bpermute_b32 v198, v232, v138
	ds_bpermute_b32 v199, v232, v139
	s_waitcnt lgkmcnt(4)
	v_mfma_f32_16x16x32_bf16 v[12:15], v[212:215], v[216:219], v[12:15]
	ds_bpermute_b32 v200, v232, v140
	ds_bpermute_b32 v201, v232, v141
	ds_bpermute_b32 v202, v232, v142
	ds_bpermute_b32 v203, v232, v143
	s_waitcnt vmcnt(30)
	ds_bpermute_b32 v204, v232, v144
	ds_bpermute_b32 v205, v232, v145
	ds_bpermute_b32 v206, v232, v146
	ds_bpermute_b32 v207, v232, v147
	s_waitcnt lgkmcnt(4)
	v_mfma_f32_16x16x32_bf16 v[12:15], v[196:199], v[200:203], v[12:15]
	ds_bpermute_b32 v208, v232, v148
	ds_bpermute_b32 v209, v232, v149
	ds_bpermute_b32 v210, v232, v150
	ds_bpermute_b32 v211, v232, v151
	s_waitcnt vmcnt(28)
	ds_bpermute_b32 v212, v232, v156
	ds_bpermute_b32 v213, v232, v157
	ds_bpermute_b32 v214, v232, v158
	ds_bpermute_b32 v215, v232, v159
	s_waitcnt lgkmcnt(4)
	v_mfma_f32_16x16x32_bf16 v[12:15], v[204:207], v[208:211], v[12:15]
	ds_bpermute_b32 v216, v232, v160
	ds_bpermute_b32 v217, v232, v161
	ds_bpermute_b32 v218, v232, v162
	ds_bpermute_b32 v219, v232, v163
	s_waitcnt vmcnt(26)
	ds_bpermute_b32 v196, v232, v164
	ds_bpermute_b32 v197, v232, v165
	ds_bpermute_b32 v198, v232, v166
	ds_bpermute_b32 v199, v232, v167
	s_waitcnt lgkmcnt(4)
	v_mfma_f32_16x16x32_bf16 v[12:15], v[212:215], v[216:219], v[12:15]
	ds_bpermute_b32 v200, v232, v168
	ds_bpermute_b32 v201, v232, v169
	ds_bpermute_b32 v202, v232, v170
	ds_bpermute_b32 v203, v232, v171
	s_waitcnt vmcnt(24)
	ds_bpermute_b32 v204, v232, v172
	ds_bpermute_b32 v205, v232, v173
	ds_bpermute_b32 v206, v232, v174
	ds_bpermute_b32 v207, v232, v175
	s_waitcnt lgkmcnt(4)
	v_mfma_f32_16x16x32_bf16 v[12:15], v[196:199], v[200:203], v[12:15]
	ds_bpermute_b32 v208, v232, v176
	ds_bpermute_b32 v209, v232, v177
	ds_bpermute_b32 v210, v232, v178
	ds_bpermute_b32 v211, v232, v179
	s_waitcnt vmcnt(22)
	ds_bpermute_b32 v212, v232, v16
	ds_bpermute_b32 v213, v232, v17
	ds_bpermute_b32 v214, v232, v18
	ds_bpermute_b32 v215, v232, v19
	s_waitcnt lgkmcnt(4)
	v_mfma_f32_16x16x32_bf16 v[12:15], v[204:207], v[208:211], v[12:15]
	ds_bpermute_b32 v216, v232, v20
	ds_bpermute_b32 v217, v232, v21
	ds_bpermute_b32 v218, v232, v22
	ds_bpermute_b32 v219, v232, v23
	s_waitcnt vmcnt(20)
	ds_bpermute_b32 v196, v232, v24
	ds_bpermute_b32 v197, v232, v25
	ds_bpermute_b32 v198, v232, v26
	ds_bpermute_b32 v199, v232, v27
	s_waitcnt lgkmcnt(4)
	v_mfma_f32_16x16x32_bf16 v[12:15], v[212:215], v[216:219], v[12:15]
	ds_bpermute_b32 v200, v232, v28
	ds_bpermute_b32 v201, v232, v29
	ds_bpermute_b32 v202, v232, v30
	ds_bpermute_b32 v203, v232, v31
	s_waitcnt vmcnt(18)
	ds_bpermute_b32 v204, v232, v32
	ds_bpermute_b32 v205, v232, v33
	ds_bpermute_b32 v206, v232, v34
	ds_bpermute_b32 v207, v232, v35
	s_waitcnt lgkmcnt(4)
	v_mfma_f32_16x16x32_bf16 v[12:15], v[196:199], v[200:203], v[12:15]
	ds_bpermute_b32 v208, v232, v36
	ds_bpermute_b32 v209, v232, v37
	ds_bpermute_b32 v210, v232, v38
	ds_bpermute_b32 v211, v232, v39
	s_waitcnt vmcnt(16)
	ds_bpermute_b32 v212, v232, v40
	ds_bpermute_b32 v213, v232, v41
	ds_bpermute_b32 v214, v232, v42
	ds_bpermute_b32 v215, v232, v43
	s_waitcnt lgkmcnt(4)
	v_mfma_f32_16x16x32_bf16 v[12:15], v[204:207], v[208:211], v[12:15]
	ds_bpermute_b32 v216, v232, v44
	ds_bpermute_b32 v217, v232, v45
	ds_bpermute_b32 v218, v232, v46
	ds_bpermute_b32 v219, v232, v47
	s_waitcnt vmcnt(14)
	ds_bpermute_b32 v196, v232, v48
	ds_bpermute_b32 v197, v232, v49
	ds_bpermute_b32 v198, v232, v50
	ds_bpermute_b32 v199, v232, v51
	s_waitcnt lgkmcnt(4)
	v_mfma_f32_16x16x32_bf16 v[12:15], v[212:215], v[216:219], v[12:15]
	ds_bpermute_b32 v200, v232, v52
	ds_bpermute_b32 v201, v232, v53
	ds_bpermute_b32 v202, v232, v54
	ds_bpermute_b32 v203, v232, v55
	s_waitcnt vmcnt(12)
	ds_bpermute_b32 v204, v232, v56
	ds_bpermute_b32 v205, v232, v57
	ds_bpermute_b32 v206, v232, v58
	ds_bpermute_b32 v207, v232, v59
	s_waitcnt lgkmcnt(4)
	v_mfma_f32_16x16x32_bf16 v[12:15], v[196:199], v[200:203], v[12:15]
	ds_bpermute_b32 v208, v232, v60
	ds_bpermute_b32 v209, v232, v61
	ds_bpermute_b32 v210, v232, v62
	ds_bpermute_b32 v211, v232, v63
	s_waitcnt vmcnt(10)
	ds_bpermute_b32 v212, v232, v64
	ds_bpermute_b32 v213, v232, v65
	ds_bpermute_b32 v214, v232, v66
	ds_bpermute_b32 v215, v232, v67
	s_waitcnt lgkmcnt(4)
	v_mfma_f32_16x16x32_bf16 v[12:15], v[204:207], v[208:211], v[12:15]
	ds_bpermute_b32 v216, v232, v68
	ds_bpermute_b32 v217, v232, v69
	ds_bpermute_b32 v218, v232, v70
	ds_bpermute_b32 v219, v232, v71
	s_waitcnt vmcnt(8)
	ds_bpermute_b32 v196, v232, v72
	ds_bpermute_b32 v197, v232, v73
	ds_bpermute_b32 v198, v232, v74
	ds_bpermute_b32 v199, v232, v75
	s_waitcnt lgkmcnt(4)
	v_mfma_f32_16x16x32_bf16 v[12:15], v[212:215], v[216:219], v[12:15]
	ds_bpermute_b32 v200, v232, v76
	ds_bpermute_b32 v201, v232, v77
	ds_bpermute_b32 v202, v232, v78
	ds_bpermute_b32 v203, v232, v79
	s_waitcnt vmcnt(6)
	ds_bpermute_b32 v204, v232, v80
	ds_bpermute_b32 v205, v232, v81
	ds_bpermute_b32 v206, v232, v82
	ds_bpermute_b32 v207, v232, v83
	s_waitcnt lgkmcnt(4)
	v_mfma_f32_16x16x32_bf16 v[12:15], v[196:199], v[200:203], v[12:15]
	ds_bpermute_b32 v208, v232, v84
	ds_bpermute_b32 v209, v232, v85
	ds_bpermute_b32 v210, v232, v86
	ds_bpermute_b32 v211, v232, v87
	s_waitcnt vmcnt(4)
	ds_bpermute_b32 v212, v232, v88
	ds_bpermute_b32 v213, v232, v89
	ds_bpermute_b32 v214, v232, v90
	ds_bpermute_b32 v215, v232, v91
	s_waitcnt lgkmcnt(4)
	v_mfma_f32_16x16x32_bf16 v[12:15], v[204:207], v[208:211], v[12:15]
	ds_bpermute_b32 v216, v232, v92
	ds_bpermute_b32 v217, v232, v93
	ds_bpermute_b32 v218, v232, v94
	ds_bpermute_b32 v219, v232, v95
	s_waitcnt vmcnt(2)
	ds_bpermute_b32 v196, v232, v96
	ds_bpermute_b32 v197, v232, v97
	ds_bpermute_b32 v198, v232, v98
	ds_bpermute_b32 v199, v232, v99
	s_waitcnt lgkmcnt(4)
	v_mfma_f32_16x16x32_bf16 v[12:15], v[212:215], v[216:219], v[12:15]
	ds_bpermute_b32 v200, v232, v100
	ds_bpermute_b32 v201, v232, v101
	ds_bpermute_b32 v202, v232, v102
	ds_bpermute_b32 v203, v232, v103
	s_waitcnt vmcnt(0)
	ds_bpermute_b32 v204, v232, v104
	ds_bpermute_b32 v205, v232, v105
	ds_bpermute_b32 v206, v232, v106
	ds_bpermute_b32 v207, v232, v107
	s_waitcnt lgkmcnt(4)
	v_mfma_f32_16x16x32_bf16 v[12:15], v[196:199], v[200:203], v[12:15]
	ds_bpermute_b32 v208, v232, v108
	ds_bpermute_b32 v209, v232, v109
	ds_bpermute_b32 v210, v232, v110
	ds_bpermute_b32 v211, v232, v111
	s_waitcnt lgkmcnt(0)
	v_mfma_f32_16x16x32_bf16 v[12:15], v[204:207], v[208:211], v[12:15]
	s_and_b32 s4, s9, -16
	s_andn2_b64 vcc, exec, s[0:1]
	v_add_u32_e32 v36, s8, v8
	s_barrier
	s_nop 7
	ds_write_b128 v11, v[12:15]
	ds_write_b32 v36, v155 offset:32768
	s_waitcnt lgkmcnt(0)
	s_barrier
	s_cbranch_vccnz .LBB0_558
	s_ashr_i32 s5, s4, 31
	v_lshl_add_u64 v[12:13], s[4:5], 2, v[6:7]
	v_lshl_or_b32 v154, s11, 12, v10
	v_lshl_add_u64 v[28:29], v[12:13], 0, v[154:155]
	v_add_co_u32_e32 v30, vcc, s96, v28
	s_nop 1
	v_addc_co_u32_e32 v31, vcc, 0, v29, vcc
	v_add_co_u32_e32 v32, vcc, 0x3000, v28
	v_addc_co_u32_e32 v33, vcc, 0, v29, vcc
	ds_read_b128 v[12:15], v11
	ds_read_b128 v[16:19], v11 offset:2048
	ds_read_b128 v[20:23], v11 offset:4096
	ds_read_b128 v[24:27], v11 offset:6144
	s_waitcnt lgkmcnt(2)
	v_add_f32_e32 v12, v12, v16
	v_add_f32_e32 v13, v13, v17
	s_waitcnt lgkmcnt(0)
	v_add_f32_e32 v16, v20, v24
	v_add_f32_e32 v17, v21, v25
	v_add_f32_e32 v12, v12, v16
	v_add_f32_e32 v14, v14, v18
	v_add_f32_e32 v18, v22, v26
	v_add_f32_e32 v15, v15, v19
	v_add_f32_e32 v19, v23, v27
	v_add_f32_e32 v13, v13, v17
	v_add_f32_e32 v14, v14, v18
	v_add_f32_e32 v15, v15, v19
	s_waitcnt vmcnt(3)
	v_add_f32_e32 v12, v234, v12
	global_store_dword v[28:29], v12, off
	s_waitcnt vmcnt(3)
	v_add_f32_e32 v12, v13, v236
	s_waitcnt vmcnt(2)
	v_add_f32_e32 v13, v14, v238
	global_store_dword v[30:31], v12, off offset:-4096
	global_store_dword v[30:31], v13, off
	s_waitcnt vmcnt(3)
	v_add_f32_e32 v12, v15, v240
	global_store_dword v[32:33], v12, off
	s_branch .LBB0_558

.LBB0_964:
	s_and_b32 s4, s10, 0x60
	s_or_b32 s11, s4, s7
	s_and_b32 s98, s9, -16
	s_ashr_i32 s99, s98, 31
	v_lshl_or_b32 v194, s11, 12, v30
	v_lshl_add_u64 v[180:181], s[98:99], 2, v[24:25]
	v_lshl_add_u64 v[180:181], v[180:181], 0, v[194:195]
	s_mov_b32 s98, 0x3000
	s_mov_b32 s99, 0
	v_lshl_add_u64 v[182:183], v[180:181], 0, s[98:99]
	s_mov_b32 s98, 0x1000
	v_lshl_add_u64 v[180:181], v[180:181], 0, s[98:99]
	global_load_dword v176, v[180:181], off offset:-4096
	global_load_dword v177, v[180:181], off
	global_load_dword v178, v[182:183], off offset:-4096
	global_load_dword v179, v[182:183], off
	v_readfirstlane_b32 s12, v22
	v_readfirstlane_b32 s13, v23
	v_readfirstlane_b32 s14, v26
	v_readfirstlane_b32 s15, v27
	s_and_b32 s16, s9, -16
	v_and_b32_e32 v251, 63, v0
	v_lshrrev_b32_e32 v250, 2, v251
	v_and_b32_e32 v243, 3, v251
	v_add_u32_e32 v246, s16, v250
	v_lshlrev_b32_e32 v246, 11, v246
	v_lshl_add_u32 v246, v243, 4, v246
	v_add_u32_e32 v251, s11, v250
	v_lshlrev_b32_e32 v251, 12, v251
	v_lshl_add_u32 v243, v243, 5, v251
	v_and_b32_e32 v251, 63, v0
	v_and_b32_e32 v250, 15, v251
	v_lshrrev_b32_e32 v251, 4, v251
	v_lshl_add_u32 v250, v250, 2, v251
	v_lshlrev_b32_e32 v250, 2, v250
	v_mov_b32_e32 v6, 0
	global_load_dwordx4 v[32:35], v243, s[12:13]
	global_load_dwordx4 v[36:39], v243, s[12:13] offset:16
	global_load_dwordx4 v[40:43], v246, s[14:15]
	global_load_dwordx4 v[44:47], v243, s[12:13] offset:128
	global_load_dwordx4 v[48:51], v243, s[12:13] offset:144
	global_load_dwordx4 v[52:55], v246, s[14:15] offset:64
	global_load_dwordx4 v[56:59], v243, s[12:13] offset:256
	global_load_dwordx4 v[60:63], v243, s[12:13] offset:272
	global_load_dwordx4 v[64:67], v246, s[14:15] offset:128
	global_load_dwordx4 v[68:71], v243, s[12:13] offset:384
	global_load_dwordx4 v[72:75], v243, s[12:13] offset:400
	global_load_dwordx4 v[76:79], v246, s[14:15] offset:192
	global_load_dwordx4 v[80:83], v243, s[12:13] offset:512
	global_load_dwordx4 v[84:87], v243, s[12:13] offset:528
	global_load_dwordx4 v[88:91], v246, s[14:15] offset:256
	global_load_dwordx4 v[92:95], v243, s[12:13] offset:640
	global_load_dwordx4 v[96:99], v243, s[12:13] offset:656
	global_load_dwordx4 v[100:103], v246, s[14:15] offset:320
	global_load_dwordx4 v[104:107], v243, s[12:13] offset:768
	global_load_dwordx4 v[108:111], v243, s[12:13] offset:784
	global_load_dwordx4 v[112:115], v246, s[14:15] offset:384
	global_load_dwordx4 v[116:119], v243, s[12:13] offset:896
	global_load_dwordx4 v[120:123], v243, s[12:13] offset:912
	global_load_dwordx4 v[124:127], v246, s[14:15] offset:448
	s_waitcnt vmcnt(21)
	ds_bpermute_b32 v206, v250, v32
	ds_bpermute_b32 v207, v250, v33
	ds_bpermute_b32 v208, v250, v34
	ds_bpermute_b32 v209, v250, v35
	ds_bpermute_b32 v210, v250, v36
	ds_bpermute_b32 v211, v250, v37
	ds_bpermute_b32 v212, v250, v38
	ds_bpermute_b32 v213, v250, v39
	ds_bpermute_b32 v214, v250, v40
	ds_bpermute_b32 v215, v250, v41
	ds_bpermute_b32 v216, v250, v42
	ds_bpermute_b32 v217, v250, v43
	s_waitcnt lgkmcnt(4)
	v_fmac_f32_e32 v6, v206, v206
	v_fmac_f32_e32 v6, v207, v207
	v_fmac_f32_e32 v6, v208, v208
	v_fmac_f32_e32 v6, v209, v209
	v_fmac_f32_e32 v6, v210, v210
	v_fmac_f32_e32 v6, v211, v211
	v_fmac_f32_e32 v6, v212, v212
	v_fmac_f32_e32 v6, v213, v213
	v_cvt_pk_bf16_f32 v206, v206, v207
	v_cvt_pk_bf16_f32 v207, v208, v209
	v_cvt_pk_bf16_f32 v208, v210, v211
	v_cvt_pk_bf16_f32 v209, v212, v213
	s_waitcnt vmcnt(18)
	ds_bpermute_b32 v218, v250, v44
	ds_bpermute_b32 v219, v250, v45
	ds_bpermute_b32 v220, v250, v46
	ds_bpermute_b32 v221, v250, v47
	ds_bpermute_b32 v222, v250, v48
	ds_bpermute_b32 v223, v250, v49
	ds_bpermute_b32 v224, v250, v50
	ds_bpermute_b32 v225, v250, v51
	s_waitcnt lgkmcnt(8)
	v_mfma_f32_16x16x32_bf16 v[2:5], v[206:209], v[214:217], 0
	ds_bpermute_b32 v226, v250, v52
	ds_bpermute_b32 v227, v250, v53
	ds_bpermute_b32 v228, v250, v54
	ds_bpermute_b32 v229, v250, v55
	s_waitcnt lgkmcnt(4)
	v_fmac_f32_e32 v6, v218, v218
	v_fmac_f32_e32 v6, v219, v219
	v_fmac_f32_e32 v6, v220, v220
	v_fmac_f32_e32 v6, v221, v221
	v_fmac_f32_e32 v6, v222, v222
	v_fmac_f32_e32 v6, v223, v223
	v_fmac_f32_e32 v6, v224, v224
	v_fmac_f32_e32 v6, v225, v225
	v_cvt_pk_bf16_f32 v218, v218, v219
	v_cvt_pk_bf16_f32 v219, v220, v221
	v_cvt_pk_bf16_f32 v220, v222, v223
	v_cvt_pk_bf16_f32 v221, v224, v225
	s_waitcnt vmcnt(15)
	ds_bpermute_b32 v206, v250, v56
	ds_bpermute_b32 v207, v250, v57
	ds_bpermute_b32 v208, v250, v58
	ds_bpermute_b32 v209, v250, v59
	ds_bpermute_b32 v210, v250, v60
	ds_bpermute_b32 v211, v250, v61
	ds_bpermute_b32 v212, v250, v62
	ds_bpermute_b32 v213, v250, v63
	s_waitcnt lgkmcnt(8)
	v_mfma_f32_16x16x32_bf16 v[2:5], v[218:221], v[226:229], v[2:5]
	ds_bpermute_b32 v214, v250, v64
	ds_bpermute_b32 v215, v250, v65
	ds_bpermute_b32 v216, v250, v66
	ds_bpermute_b32 v217, v250, v67
	s_waitcnt lgkmcnt(4)
	v_fmac_f32_e32 v6, v206, v206
	v_fmac_f32_e32 v6, v207, v207
	v_fmac_f32_e32 v6, v208, v208
	v_fmac_f32_e32 v6, v209, v209
	v_fmac_f32_e32 v6, v210, v210
	v_fmac_f32_e32 v6, v211, v211
	v_fmac_f32_e32 v6, v212, v212
	v_fmac_f32_e32 v6, v213, v213
	v_cvt_pk_bf16_f32 v206, v206, v207
	v_cvt_pk_bf16_f32 v207, v208, v209
	v_cvt_pk_bf16_f32 v208, v210, v211
	v_cvt_pk_bf16_f32 v209, v212, v213
	s_waitcnt vmcnt(12)
	ds_bpermute_b32 v218, v250, v68
	ds_bpermute_b32 v219, v250, v69
	ds_bpermute_b32 v220, v250, v70
	ds_bpermute_b32 v221, v250, v71
	ds_bpermute_b32 v222, v250, v72
	ds_bpermute_b32 v223, v250, v73
	ds_bpermute_b32 v224, v250, v74
	ds_bpermute_b32 v225, v250, v75
	s_waitcnt lgkmcnt(8)
	v_mfma_f32_16x16x32_bf16 v[2:5], v[206:209], v[214:217], v[2:5]
	ds_bpermute_b32 v226, v250, v76
	ds_bpermute_b32 v227, v250, v77
	ds_bpermute_b32 v228, v250, v78
	ds_bpermute_b32 v229, v250, v79
	s_waitcnt lgkmcnt(4)
	v_fmac_f32_e32 v6, v218, v218
	v_fmac_f32_e32 v6, v219, v219
	v_fmac_f32_e32 v6, v220, v220
	v_fmac_f32_e32 v6, v221, v221
	v_fmac_f32_e32 v6, v222, v222
	v_fmac_f32_e32 v6, v223, v223
	v_fmac_f32_e32 v6, v224, v224
	v_fmac_f32_e32 v6, v225, v225
	v_cvt_pk_bf16_f32 v218, v218, v219
	v_cvt_pk_bf16_f32 v219, v220, v221
	v_cvt_pk_bf16_f32 v220, v222, v223
	v_cvt_pk_bf16_f32 v221, v224, v225
	s_waitcnt vmcnt(9)
	ds_bpermute_b32 v206, v250, v80
	ds_bpermute_b32 v207, v250, v81
	ds_bpermute_b32 v208, v250, v82
	ds_bpermute_b32 v209, v250, v83
	ds_bpermute_b32 v210, v250, v84
	ds_bpermute_b32 v211, v250, v85
	ds_bpermute_b32 v212, v250, v86
	ds_bpermute_b32 v213, v250, v87
	s_waitcnt lgkmcnt(8)
	v_mfma_f32_16x16x32_bf16 v[2:5], v[218:221], v[226:229], v[2:5]
	ds_bpermute_b32 v214, v250, v88
	ds_bpermute_b32 v215, v250, v89
	ds_bpermute_b32 v216, v250, v90
	ds_bpermute_b32 v217, v250, v91
	s_waitcnt lgkmcnt(4)
	v_fmac_f32_e32 v6, v206, v206
	v_fmac_f32_e32 v6, v207, v207
	v_fmac_f32_e32 v6, v208, v208
	v_fmac_f32_e32 v6, v209, v209
	v_fmac_f32_e32 v6, v210, v210
	v_fmac_f32_e32 v6, v211, v211
	v_fmac_f32_e32 v6, v212, v212
	v_fmac_f32_e32 v6, v213, v213
	v_cvt_pk_bf16_f32 v206, v206, v207
	v_cvt_pk_bf16_f32 v207, v208, v209
	v_cvt_pk_bf16_f32 v208, v210, v211
	v_cvt_pk_bf16_f32 v209, v212, v213
	s_waitcnt vmcnt(6)
	ds_bpermute_b32 v218, v250, v92
	ds_bpermute_b32 v219, v250, v93
	ds_bpermute_b32 v220, v250, v94
	ds_bpermute_b32 v221, v250, v95
	ds_bpermute_b32 v222, v250, v96
	ds_bpermute_b32 v223, v250, v97
	ds_bpermute_b32 v224, v250, v98
	ds_bpermute_b32 v225, v250, v99
	s_waitcnt lgkmcnt(8)
	v_mfma_f32_16x16x32_bf16 v[2:5], v[206:209], v[214:217], v[2:5]
	ds_bpermute_b32 v226, v250, v100
	ds_bpermute_b32 v227, v250, v101
	ds_bpermute_b32 v228, v250, v102
	ds_bpermute_b32 v229, v250, v103
	s_waitcnt lgkmcnt(4)
	v_fmac_f32_e32 v6, v218, v218
	v_fmac_f32_e32 v6, v219, v219
	v_fmac_f32_e32 v6, v220, v220
	v_fmac_f32_e32 v6, v221, v221
	v_fmac_f32_e32 v6, v222, v222
	v_fmac_f32_e32 v6, v223, v223
	v_fmac_f32_e32 v6, v224, v224
	v_fmac_f32_e32 v6, v225, v225
	v_cvt_pk_bf16_f32 v218, v218, v219
	v_cvt_pk_bf16_f32 v219, v220, v221
	v_cvt_pk_bf16_f32 v220, v222, v223
	v_cvt_pk_bf16_f32 v221, v224, v225
	s_waitcnt vmcnt(3)
	ds_bpermute_b32 v206, v250, v104
	ds_bpermute_b32 v207, v250, v105
	ds_bpermute_b32 v208, v250, v106
	ds_bpermute_b32 v209, v250, v107
	ds_bpermute_b32 v210, v250, v108
	ds_bpermute_b32 v211, v250, v109
	ds_bpermute_b32 v212, v250, v110
	ds_bpermute_b32 v213, v250, v111
	s_waitcnt lgkmcnt(8)
	v_mfma_f32_16x16x32_bf16 v[2:5], v[218:221], v[226:229], v[2:5]
	ds_bpermute_b32 v214, v250, v112
	ds_bpermute_b32 v215, v250, v113
	ds_bpermute_b32 v216, v250, v114
	ds_bpermute_b32 v217, v250, v115
	s_waitcnt lgkmcnt(4)
	v_fmac_f32_e32 v6, v206, v206
	v_fmac_f32_e32 v6, v207, v207
	v_fmac_f32_e32 v6, v208, v208
	v_fmac_f32_e32 v6, v209, v209
	v_fmac_f32_e32 v6, v210, v210
	v_fmac_f32_e32 v6, v211, v211
	v_fmac_f32_e32 v6, v212, v212
	v_fmac_f32_e32 v6, v213, v213
	v_cvt_pk_bf16_f32 v206, v206, v207
	v_cvt_pk_bf16_f32 v207, v208, v209
	v_cvt_pk_bf16_f32 v208, v210, v211
	v_cvt_pk_bf16_f32 v209, v212, v213
	s_waitcnt vmcnt(0)
	ds_bpermute_b32 v218, v250, v116
	ds_bpermute_b32 v219, v250, v117
	ds_bpermute_b32 v220, v250, v118
	ds_bpermute_b32 v221, v250, v119
	ds_bpermute_b32 v222, v250, v120
	ds_bpermute_b32 v223, v250, v121
	ds_bpermute_b32 v224, v250, v122
	ds_bpermute_b32 v225, v250, v123
	s_waitcnt lgkmcnt(8)
	v_mfma_f32_16x16x32_bf16 v[2:5], v[206:209], v[214:217], v[2:5]
	ds_bpermute_b32 v226, v250, v124
	ds_bpermute_b32 v227, v250, v125
	ds_bpermute_b32 v228, v250, v126
	ds_bpermute_b32 v229, v250, v127
	s_waitcnt lgkmcnt(4)
	v_fmac_f32_e32 v6, v218, v218
	v_fmac_f32_e32 v6, v219, v219
	v_fmac_f32_e32 v6, v220, v220
	v_fmac_f32_e32 v6, v221, v221
	v_fmac_f32_e32 v6, v222, v222
	v_fmac_f32_e32 v6, v223, v223
	v_fmac_f32_e32 v6, v224, v224
	v_fmac_f32_e32 v6, v225, v225
	v_cvt_pk_bf16_f32 v218, v218, v219
	v_cvt_pk_bf16_f32 v219, v220, v221
	v_cvt_pk_bf16_f32 v220, v222, v223
	v_cvt_pk_bf16_f32 v221, v224, v225
	s_nop 1
	s_waitcnt lgkmcnt(0)
	v_mfma_f32_16x16x32_bf16 v[2:5], v[218:221], v[226:229], v[2:5]
	v_and_b32_e32 v252, 63, v0
	v_xor_b32_e32 v254, 32, v252
	v_xor_b32_e32 v252, 16, v252
	v_lshlrev_b32_e32 v252, 2, v252
	v_lshlrev_b32_e32 v254, 2, v254
	ds_bpermute_b32 v251, v252, v6
	s_waitcnt lgkmcnt(0)
	v_add_f32_e32 v6, v6, v251
	ds_bpermute_b32 v251, v254, v6
	s_waitcnt lgkmcnt(0)
	v_add_f32_e32 v6, v6, v251
	s_and_b32 s4, s9, -16
	s_barrier
	s_andn2_b64 vcc, exec, s[0:1]
	s_nop 7
	ds_write_b128 v31, v[2:5]
	v_add_u32_e32 v2, s8, v28
	ds_write_b32 v2, v6 offset:32768
	s_waitcnt lgkmcnt(0)
	s_barrier
	s_cbranch_vccnz .LBB0_963
	s_ashr_i32 s5, s4, 31
	v_lshl_add_u64 v[2:3], s[4:5], 2, v[24:25]
	v_lshl_or_b32 v194, s11, 12, v30
	v_lshl_add_u64 v[18:19], v[2:3], 0, v[194:195]
	s_movk_i32 s4, 0x2000
	v_add_co_u32_e32 v20, vcc, s4, v18
	s_nop 1
	v_addc_co_u32_e32 v21, vcc, 0, v19, vcc
	v_add_co_u32_e32 v32, vcc, 0x3000, v18
	v_addc_co_u32_e32 v33, vcc, 0, v19, vcc
	ds_read_b128 v[2:5], v31
	ds_read_b128 v[6:9], v31 offset:2048
	ds_read_b128 v[10:13], v31 offset:4096
	ds_read_b128 v[14:17], v31 offset:6144
	s_waitcnt lgkmcnt(2)
	v_add_f32_e32 v2, v2, v6
	v_add_f32_e32 v3, v3, v7
	s_waitcnt lgkmcnt(0)
	v_add_f32_e32 v6, v10, v14
	v_add_f32_e32 v7, v11, v15
	v_add_f32_e32 v2, v2, v6
	v_add_f32_e32 v4, v4, v8
	v_add_f32_e32 v8, v12, v16
	v_add_f32_e32 v5, v5, v9
	v_add_f32_e32 v9, v13, v17
	v_add_f32_e32 v3, v3, v7
	v_add_f32_e32 v4, v4, v8
	v_add_f32_e32 v5, v5, v9
	s_waitcnt vmcnt(3)
	v_add_f32_e32 v2, v176, v2
	global_store_dword v[18:19], v2, off
	s_waitcnt vmcnt(3)
	v_add_f32_e32 v2, v3, v177
	s_waitcnt vmcnt(2)
	v_add_f32_e32 v3, v4, v178
	global_store_dword v[20:21], v2, off offset:-4096
	global_store_dword v[20:21], v3, off
	s_waitcnt vmcnt(3)
	v_add_f32_e32 v2, v5, v179
	global_store_dword v[32:33], v2, off
	s_branch .LBB0_963

.LBB0_1234:
	s_and_b32 s4, s10, 0x60
	s_or_b32 s11, s4, s7
	s_and_b32 s98, s9, -16
	s_ashr_i32 s99, s98, 31
	v_lshl_or_b32 v194, s11, 12, v10
	v_lshl_add_u64 v[180:181], s[98:99], 2, v[6:7]
	v_lshl_add_u64 v[180:181], v[180:181], 0, v[194:195]
	s_mov_b32 s98, 0x3000
	s_mov_b32 s99, 0
	v_lshl_add_u64 v[182:183], v[180:181], 0, s[98:99]
	s_mov_b32 s98, 0x1000
	v_lshl_add_u64 v[180:181], v[180:181], 0, s[98:99]
	global_load_dword v176, v[180:181], off offset:-4096
	global_load_dword v177, v[180:181], off
	global_load_dword v178, v[182:183], off offset:-4096
	global_load_dword v179, v[182:183], off
	v_readfirstlane_b32 s12, v4
	v_readfirstlane_b32 s13, v5
	v_readfirstlane_b32 s14, v2
	v_readfirstlane_b32 s15, v3
	s_and_b32 s16, s9, -16
	v_and_b32_e32 v249, 63, v0
	v_lshrrev_b32_e32 v248, 2, v249
	v_and_b32_e32 v246, 3, v249
	v_lshlrev_b32_e32 v246, 4, v246
	v_add_u32_e32 v247, s16, v248
	v_lshl_add_u32 v247, v247, 13, v246
	v_add_u32_e32 v249, s11, v248
	v_lshl_add_u32 v246, v249, 13, v246
	v_and_b32_e32 v249, 63, v0
	v_and_b32_e32 v248, 15, v249
	v_lshrrev_b32_e32 v249, 4, v249
	v_lshl_add_u32 v248, v248, 2, v249
	v_lshlrev_b32_e32 v248, 2, v248
	global_load_dwordx4 v[16:19], v246, s[12:13]
	global_load_dwordx4 v[20:23], v247, s[14:15]
	global_load_dwordx4 v[24:27], v246, s[12:13] offset:64
	global_load_dwordx4 v[28:31], v247, s[14:15] offset:64
	global_load_dwordx4 v[32:35], v246, s[12:13] offset:128
	global_load_dwordx4 v[36:39], v247, s[14:15] offset:128
	global_load_dwordx4 v[40:43], v246, s[12:13] offset:192
	global_load_dwordx4 v[44:47], v247, s[14:15] offset:192
	global_load_dwordx4 v[48:51], v246, s[12:13] offset:256
	global_load_dwordx4 v[52:55], v247, s[14:15] offset:256
	global_load_dwordx4 v[56:59], v246, s[12:13] offset:320
	global_load_dwordx4 v[60:63], v247, s[14:15] offset:320
	global_load_dwordx4 v[64:67], v246, s[12:13] offset:384
	global_load_dwordx4 v[68:71], v247, s[14:15] offset:384
	global_load_dwordx4 v[72:75], v246, s[12:13] offset:448
	global_load_dwordx4 v[76:79], v247, s[14:15] offset:448
	global_load_dwordx4 v[80:83], v246, s[12:13] offset:512
	global_load_dwordx4 v[84:87], v247, s[14:15] offset:512
	global_load_dwordx4 v[88:91], v246, s[12:13] offset:576
	global_load_dwordx4 v[92:95], v247, s[14:15] offset:576
	global_load_dwordx4 v[96:99], v246, s[12:13] offset:640
	global_load_dwordx4 v[100:103], v247, s[14:15] offset:640
	global_load_dwordx4 v[104:107], v246, s[12:13] offset:704
	global_load_dwordx4 v[108:111], v247, s[14:15] offset:704
	global_load_dwordx4 v[112:115], v246, s[12:13] offset:768
	global_load_dwordx4 v[116:119], v247, s[14:15] offset:768
	global_load_dwordx4 v[120:123], v246, s[12:13] offset:832
	global_load_dwordx4 v[124:127], v247, s[14:15] offset:832
	global_load_dwordx4 v[128:131], v246, s[12:13] offset:896
	global_load_dwordx4 v[132:135], v247, s[14:15] offset:896
	global_load_dwordx4 v[136:139], v246, s[12:13] offset:960
	global_load_dwordx4 v[140:143], v247, s[14:15] offset:960
	global_load_dwordx4 v[144:147], v246, s[12:13] offset:1024
	global_load_dwordx4 v[148:151], v247, s[14:15] offset:1024
	global_load_dwordx4 v[152:155], v246, s[12:13] offset:1088
	global_load_dwordx4 v[156:159], v247, s[14:15] offset:1088
	global_load_dwordx4 v[160:163], v246, s[12:13] offset:1152
	global_load_dwordx4 v[164:167], v247, s[14:15] offset:1152
	global_load_dwordx4 v[168:171], v246, s[12:13] offset:1216
	global_load_dwordx4 v[172:175], v247, s[14:15] offset:1216
	s_waitcnt vmcnt(38)
	ds_bpermute_b32 v206, v248, v16
	ds_bpermute_b32 v207, v248, v17
	ds_bpermute_b32 v208, v248, v18
	ds_bpermute_b32 v209, v248, v19
	ds_bpermute_b32 v210, v248, v20
	ds_bpermute_b32 v211, v248, v21
	ds_bpermute_b32 v212, v248, v22
	ds_bpermute_b32 v213, v248, v23
	global_load_dwordx4 v[16:19], v246, s[12:13] offset:1280
	global_load_dwordx4 v[20:23], v247, s[14:15] offset:1280
	s_waitcnt vmcnt(38)
	ds_bpermute_b32 v214, v248, v24
	ds_bpermute_b32 v215, v248, v25
	ds_bpermute_b32 v216, v248, v26
	ds_bpermute_b32 v217, v248, v27
	s_waitcnt lgkmcnt(4)
	v_mfma_f32_16x16x32_bf16 v[12:15], v[206:209], v[210:213], 0
	ds_bpermute_b32 v218, v248, v28
	ds_bpermute_b32 v219, v248, v29
	ds_bpermute_b32 v220, v248, v30
	ds_bpermute_b32 v221, v248, v31
	global_load_dwordx4 v[24:27], v246, s[12:13] offset:1344
	global_load_dwordx4 v[28:31], v247, s[14:15] offset:1344
	s_waitcnt vmcnt(38)
	ds_bpermute_b32 v222, v248, v32
	ds_bpermute_b32 v223, v248, v33
	ds_bpermute_b32 v224, v248, v34
	ds_bpermute_b32 v225, v248, v35
	s_waitcnt lgkmcnt(4)
	v_mfma_f32_16x16x32_bf16 v[12:15], v[214:217], v[218:221], v[12:15]
	ds_bpermute_b32 v226, v248, v36
	ds_bpermute_b32 v227, v248, v37
	ds_bpermute_b32 v228, v248, v38
	ds_bpermute_b32 v229, v248, v39
	global_load_dwordx4 v[32:35], v246, s[12:13] offset:1408
	global_load_dwordx4 v[36:39], v247, s[14:15] offset:1408
	s_waitcnt vmcnt(38)
	ds_bpermute_b32 v206, v248, v40
	ds_bpermute_b32 v207, v248, v41
	ds_bpermute_b32 v208, v248, v42
	ds_bpermute_b32 v209, v248, v43
	s_waitcnt lgkmcnt(4)
	v_mfma_f32_16x16x32_bf16 v[12:15], v[222:225], v[226:229], v[12:15]
	ds_bpermute_b32 v210, v248, v44
	ds_bpermute_b32 v211, v248, v45
	ds_bpermute_b32 v212, v248, v46
	ds_bpermute_b32 v213, v248, v47
	global_load_dwordx4 v[40:43], v246, s[12:13] offset:1472
	global_load_dwordx4 v[44:47], v247, s[14:15] offset:1472
	s_waitcnt vmcnt(38)
	ds_bpermute_b32 v214, v248, v48
	ds_bpermute_b32 v215, v248, v49
	ds_bpermute_b32 v216, v248, v50
	ds_bpermute_b32 v217, v248, v51
	s_waitcnt lgkmcnt(4)
	v_mfma_f32_16x16x32_bf16 v[12:15], v[206:209], v[210:213], v[12:15]
	ds_bpermute_b32 v218, v248, v52
	ds_bpermute_b32 v219, v248, v53
	ds_bpermute_b32 v220, v248, v54
	ds_bpermute_b32 v221, v248, v55
	global_load_dwordx4 v[48:51], v246, s[12:13] offset:1536
	global_load_dwordx4 v[52:55], v247, s[14:15] offset:1536
	s_waitcnt vmcnt(38)
	ds_bpermute_b32 v222, v248, v56
	ds_bpermute_b32 v223, v248, v57
	ds_bpermute_b32 v224, v248, v58
	ds_bpermute_b32 v225, v248, v59
	s_waitcnt lgkmcnt(4)
	v_mfma_f32_16x16x32_bf16 v[12:15], v[214:217], v[218:221], v[12:15]
	ds_bpermute_b32 v226, v248, v60
	ds_bpermute_b32 v227, v248, v61
	ds_bpermute_b32 v228, v248, v62
	ds_bpermute_b32 v229, v248, v63
	global_load_dwordx4 v[56:59], v246, s[12:13] offset:1600
	global_load_dwordx4 v[60:63], v247, s[14:15] offset:1600
	s_waitcnt vmcnt(38)
	ds_bpermute_b32 v206, v248, v64
	ds_bpermute_b32 v207, v248, v65
	ds_bpermute_b32 v208, v248, v66
	ds_bpermute_b32 v209, v248, v67
	s_waitcnt lgkmcnt(4)
	v_mfma_f32_16x16x32_bf16 v[12:15], v[222:225], v[226:229], v[12:15]
	ds_bpermute_b32 v210, v248, v68
	ds_bpermute_b32 v211, v248, v69
	ds_bpermute_b32 v212, v248, v70
	ds_bpermute_b32 v213, v248, v71
	global_load_dwordx4 v[64:67], v246, s[12:13] offset:1664
	global_load_dwordx4 v[68:71], v247, s[14:15] offset:1664
	s_waitcnt vmcnt(38)
	ds_bpermute_b32 v214, v248, v72
	ds_bpermute_b32 v215, v248, v73
	ds_bpermute_b32 v216, v248, v74
	ds_bpermute_b32 v217, v248, v75
	s_waitcnt lgkmcnt(4)
	v_mfma_f32_16x16x32_bf16 v[12:15], v[206:209], v[210:213], v[12:15]
	ds_bpermute_b32 v218, v248, v76
	ds_bpermute_b32 v219, v248, v77
	ds_bpermute_b32 v220, v248, v78
	ds_bpermute_b32 v221, v248, v79
	global_load_dwordx4 v[72:75], v246, s[12:13] offset:1728
	global_load_dwordx4 v[76:79], v247, s[14:15] offset:1728
	s_waitcnt vmcnt(38)
	ds_bpermute_b32 v222, v248, v80
	ds_bpermute_b32 v223, v248, v81
	ds_bpermute_b32 v224, v248, v82
	ds_bpermute_b32 v225, v248, v83
	s_waitcnt lgkmcnt(4)
	v_mfma_f32_16x16x32_bf16 v[12:15], v[214:217], v[218:221], v[12:15]
	ds_bpermute_b32 v226, v248, v84
	ds_bpermute_b32 v227, v248, v85
	ds_bpermute_b32 v228, v248, v86
	ds_bpermute_b32 v229, v248, v87
	global_load_dwordx4 v[80:83], v246, s[12:13] offset:1792
	global_load_dwordx4 v[84:87], v247, s[14:15] offset:1792
	s_waitcnt vmcnt(38)
	ds_bpermute_b32 v206, v248, v88
	ds_bpermute_b32 v207, v248, v89
	ds_bpermute_b32 v208, v248, v90
	ds_bpermute_b32 v209, v248, v91
	s_waitcnt lgkmcnt(4)
	v_mfma_f32_16x16x32_bf16 v[12:15], v[222:225], v[226:229], v[12:15]
	ds_bpermute_b32 v210, v248, v92
	ds_bpermute_b32 v211, v248, v93
	ds_bpermute_b32 v212, v248, v94
	ds_bpermute_b32 v213, v248, v95
	global_load_dwordx4 v[88:91], v246, s[12:13] offset:1856
	global_load_dwordx4 v[92:95], v247, s[14:15] offset:1856
	s_waitcnt vmcnt(38)
	ds_bpermute_b32 v214, v248, v96
	ds_bpermute_b32 v215, v248, v97
	ds_bpermute_b32 v216, v248, v98
	ds_bpermute_b32 v217, v248, v99
	s_waitcnt lgkmcnt(4)
	v_mfma_f32_16x16x32_bf16 v[12:15], v[206:209], v[210:213], v[12:15]
	ds_bpermute_b32 v218, v248, v100
	ds_bpermute_b32 v219, v248, v101
	ds_bpermute_b32 v220, v248, v102
	ds_bpermute_b32 v221, v248, v103
	global_load_dwordx4 v[96:99], v246, s[12:13] offset:1920
	global_load_dwordx4 v[100:103], v247, s[14:15] offset:1920
	s_waitcnt vmcnt(38)
	ds_bpermute_b32 v222, v248, v104
	ds_bpermute_b32 v223, v248, v105
	ds_bpermute_b32 v224, v248, v106
	ds_bpermute_b32 v225, v248, v107
	s_waitcnt lgkmcnt(4)
	v_mfma_f32_16x16x32_bf16 v[12:15], v[214:217], v[218:221], v[12:15]
	ds_bpermute_b32 v226, v248, v108
	ds_bpermute_b32 v227, v248, v109
	ds_bpermute_b32 v228, v248, v110
	ds_bpermute_b32 v229, v248, v111
	global_load_dwordx4 v[104:107], v246, s[12:13] offset:1984
	global_load_dwordx4 v[108:111], v247, s[14:15] offset:1984
	s_waitcnt vmcnt(38)
	ds_bpermute_b32 v206, v248, v112
	ds_bpermute_b32 v207, v248, v113
	ds_bpermute_b32 v208, v248, v114
	ds_bpermute_b32 v209, v248, v115
	s_waitcnt lgkmcnt(4)
	v_mfma_f32_16x16x32_bf16 v[12:15], v[222:225], v[226:229], v[12:15]
	ds_bpermute_b32 v210, v248, v116
	ds_bpermute_b32 v211, v248, v117
	ds_bpermute_b32 v212, v248, v118
	ds_bpermute_b32 v213, v248, v119
	s_waitcnt vmcnt(36)
	ds_bpermute_b32 v214, v248, v120
	ds_bpermute_b32 v215, v248, v121
	ds_bpermute_b32 v216, v248, v122
	ds_bpermute_b32 v217, v248, v123
	s_waitcnt lgkmcnt(4)
	v_mfma_f32_16x16x32_bf16 v[12:15], v[206:209], v[210:213], v[12:15]
	ds_bpermute_b32 v218, v248, v124
	ds_bpermute_b32 v219, v248, v125
	ds_bpermute_b32 v220, v248, v126
	ds_bpermute_b32 v221, v248, v127
	s_waitcnt vmcnt(34)
	ds_bpermute_b32 v222, v248, v128
	ds_bpermute_b32 v223, v248, v129
	ds_bpermute_b32 v224, v248, v130
	ds_bpermute_b32 v225, v248, v131
	s_waitcnt lgkmcnt(4)
	v_mfma_f32_16x16x32_bf16 v[12:15], v[214:217], v[218:221], v[12:15]
	ds_bpermute_b32 v226, v248, v132
	ds_bpermute_b32 v227, v248, v133
	ds_bpermute_b32 v228, v248, v134
	ds_bpermute_b32 v229, v248, v135
	s_waitcnt vmcnt(32)
	ds_bpermute_b32 v206, v248, v136
	ds_bpermute_b32 v207, v248, v137
	ds_bpermute_b32 v208, v248, v138
	ds_bpermute_b32 v209, v248, v139
	s_waitcnt lgkmcnt(4)
	v_mfma_f32_16x16x32_bf16 v[12:15], v[222:225], v[226:229], v[12:15]
	ds_bpermute_b32 v210, v248, v140
	ds_bpermute_b32 v211, v248, v141
	ds_bpermute_b32 v212, v248, v142
	ds_bpermute_b32 v213, v248, v143
	s_waitcnt vmcnt(30)
	ds_bpermute_b32 v214, v248, v144
	ds_bpermute_b32 v215, v248, v145
	ds_bpermute_b32 v216, v248, v146
	ds_bpermute_b32 v217, v248, v147
	s_waitcnt lgkmcnt(4)
	v_mfma_f32_16x16x32_bf16 v[12:15], v[206:209], v[210:213], v[12:15]
	ds_bpermute_b32 v218, v248, v148
	ds_bpermute_b32 v219, v248, v149
	ds_bpermute_b32 v220, v248, v150
	ds_bpermute_b32 v221, v248, v151
	s_waitcnt vmcnt(28)
	ds_bpermute_b32 v222, v248, v152
	ds_bpermute_b32 v223, v248, v153
	ds_bpermute_b32 v224, v248, v154
	ds_bpermute_b32 v225, v248, v155
	s_waitcnt lgkmcnt(4)
	v_mfma_f32_16x16x32_bf16 v[12:15], v[214:217], v[218:221], v[12:15]
	ds_bpermute_b32 v226, v248, v156
	ds_bpermute_b32 v227, v248, v157
	ds_bpermute_b32 v228, v248, v158
	ds_bpermute_b32 v229, v248, v159
	s_waitcnt vmcnt(26)
	ds_bpermute_b32 v206, v248, v160
	ds_bpermute_b32 v207, v248, v161
	ds_bpermute_b32 v208, v248, v162
	ds_bpermute_b32 v209, v248, v163
	s_waitcnt lgkmcnt(4)
	v_mfma_f32_16x16x32_bf16 v[12:15], v[222:225], v[226:229], v[12:15]
	ds_bpermute_b32 v210, v248, v164
	ds_bpermute_b32 v211, v248, v165
	ds_bpermute_b32 v212, v248, v166
	ds_bpermute_b32 v213, v248, v167
	s_waitcnt vmcnt(24)
	ds_bpermute_b32 v214, v248, v168
	ds_bpermute_b32 v215, v248, v169
	ds_bpermute_b32 v216, v248, v170
	ds_bpermute_b32 v217, v248, v171
	s_waitcnt lgkmcnt(4)
	v_mfma_f32_16x16x32_bf16 v[12:15], v[206:209], v[210:213], v[12:15]
	ds_bpermute_b32 v218, v248, v172
	ds_bpermute_b32 v219, v248, v173
	ds_bpermute_b32 v220, v248, v174
	ds_bpermute_b32 v221, v248, v175
	s_waitcnt vmcnt(22)
	ds_bpermute_b32 v222, v248, v16
	ds_bpermute_b32 v223, v248, v17
	ds_bpermute_b32 v224, v248, v18
	ds_bpermute_b32 v225, v248, v19
	s_waitcnt lgkmcnt(4)
	v_mfma_f32_16x16x32_bf16 v[12:15], v[214:217], v[218:221], v[12:15]
	ds_bpermute_b32 v226, v248, v20
	ds_bpermute_b32 v227, v248, v21
	ds_bpermute_b32 v228, v248, v22
	ds_bpermute_b32 v229, v248, v23
	s_waitcnt vmcnt(20)
	ds_bpermute_b32 v206, v248, v24
	ds_bpermute_b32 v207, v248, v25
	ds_bpermute_b32 v208, v248, v26
	ds_bpermute_b32 v209, v248, v27
	s_waitcnt lgkmcnt(4)
	v_mfma_f32_16x16x32_bf16 v[12:15], v[222:225], v[226:229], v[12:15]
	ds_bpermute_b32 v210, v248, v28
	ds_bpermute_b32 v211, v248, v29
	ds_bpermute_b32 v212, v248, v30
	ds_bpermute_b32 v213, v248, v31
	s_waitcnt vmcnt(18)
	ds_bpermute_b32 v214, v248, v32
	ds_bpermute_b32 v215, v248, v33
	ds_bpermute_b32 v216, v248, v34
	ds_bpermute_b32 v217, v248, v35
	s_waitcnt lgkmcnt(4)
	v_mfma_f32_16x16x32_bf16 v[12:15], v[206:209], v[210:213], v[12:15]
	ds_bpermute_b32 v218, v248, v36
	ds_bpermute_b32 v219, v248, v37
	ds_bpermute_b32 v220, v248, v38
	ds_bpermute_b32 v221, v248, v39
	s_waitcnt vmcnt(16)
	ds_bpermute_b32 v222, v248, v40
	ds_bpermute_b32 v223, v248, v41
	ds_bpermute_b32 v224, v248, v42
	ds_bpermute_b32 v225, v248, v43
	s_waitcnt lgkmcnt(4)
	v_mfma_f32_16x16x32_bf16 v[12:15], v[214:217], v[218:221], v[12:15]
	ds_bpermute_b32 v226, v248, v44
	ds_bpermute_b32 v227, v248, v45
	ds_bpermute_b32 v228, v248, v46
	ds_bpermute_b32 v229, v248, v47
	s_waitcnt vmcnt(14)
	ds_bpermute_b32 v206, v248, v48
	ds_bpermute_b32 v207, v248, v49
	ds_bpermute_b32 v208, v248, v50
	ds_bpermute_b32 v209, v248, v51
	s_waitcnt lgkmcnt(4)
	v_mfma_f32_16x16x32_bf16 v[12:15], v[222:225], v[226:229], v[12:15]
	ds_bpermute_b32 v210, v248, v52
	ds_bpermute_b32 v211, v248, v53
	ds_bpermute_b32 v212, v248, v54
	ds_bpermute_b32 v213, v248, v55
	s_waitcnt vmcnt(12)
	ds_bpermute_b32 v214, v248, v56
	ds_bpermute_b32 v215, v248, v57
	ds_bpermute_b32 v216, v248, v58
	ds_bpermute_b32 v217, v248, v59
	s_waitcnt lgkmcnt(4)
	v_mfma_f32_16x16x32_bf16 v[12:15], v[206:209], v[210:213], v[12:15]
	ds_bpermute_b32 v218, v248, v60
	ds_bpermute_b32 v219, v248, v61
	ds_bpermute_b32 v220, v248, v62
	ds_bpermute_b32 v221, v248, v63
	s_waitcnt vmcnt(10)
	ds_bpermute_b32 v222, v248, v64
	ds_bpermute_b32 v223, v248, v65
	ds_bpermute_b32 v224, v248, v66
	ds_bpermute_b32 v225, v248, v67
	s_waitcnt lgkmcnt(4)
	v_mfma_f32_16x16x32_bf16 v[12:15], v[214:217], v[218:221], v[12:15]
	ds_bpermute_b32 v226, v248, v68
	ds_bpermute_b32 v227, v248, v69
	ds_bpermute_b32 v228, v248, v70
	ds_bpermute_b32 v229, v248, v71
	s_waitcnt vmcnt(8)
	ds_bpermute_b32 v206, v248, v72
	ds_bpermute_b32 v207, v248, v73
	ds_bpermute_b32 v208, v248, v74
	ds_bpermute_b32 v209, v248, v75
	s_waitcnt lgkmcnt(4)
	v_mfma_f32_16x16x32_bf16 v[12:15], v[222:225], v[226:229], v[12:15]
	ds_bpermute_b32 v210, v248, v76
	ds_bpermute_b32 v211, v248, v77
	ds_bpermute_b32 v212, v248, v78
	ds_bpermute_b32 v213, v248, v79
	s_waitcnt vmcnt(6)
	ds_bpermute_b32 v214, v248, v80
	ds_bpermute_b32 v215, v248, v81
	ds_bpermute_b32 v216, v248, v82
	ds_bpermute_b32 v217, v248, v83
	s_waitcnt lgkmcnt(4)
	v_mfma_f32_16x16x32_bf16 v[12:15], v[206:209], v[210:213], v[12:15]
	ds_bpermute_b32 v218, v248, v84
	ds_bpermute_b32 v219, v248, v85
	ds_bpermute_b32 v220, v248, v86
	ds_bpermute_b32 v221, v248, v87
	s_waitcnt vmcnt(4)
	ds_bpermute_b32 v222, v248, v88
	ds_bpermute_b32 v223, v248, v89
	ds_bpermute_b32 v224, v248, v90
	ds_bpermute_b32 v225, v248, v91
	s_waitcnt lgkmcnt(4)
	v_mfma_f32_16x16x32_bf16 v[12:15], v[214:217], v[218:221], v[12:15]
	ds_bpermute_b32 v226, v248, v92
	ds_bpermute_b32 v227, v248, v93
	ds_bpermute_b32 v228, v248, v94
	ds_bpermute_b32 v229, v248, v95
	s_waitcnt vmcnt(2)
	ds_bpermute_b32 v206, v248, v96
	ds_bpermute_b32 v207, v248, v97
	ds_bpermute_b32 v208, v248, v98
	ds_bpermute_b32 v209, v248, v99
	s_waitcnt lgkmcnt(4)
	v_mfma_f32_16x16x32_bf16 v[12:15], v[222:225], v[226:229], v[12:15]
	ds_bpermute_b32 v210, v248, v100
	ds_bpermute_b32 v211, v248, v101
	ds_bpermute_b32 v212, v248, v102
	ds_bpermute_b32 v213, v248, v103
	s_waitcnt vmcnt(0)
	ds_bpermute_b32 v214, v248, v104
	ds_bpermute_b32 v215, v248, v105
	ds_bpermute_b32 v216, v248, v106
	ds_bpermute_b32 v217, v248, v107
	s_waitcnt lgkmcnt(4)
	v_mfma_f32_16x16x32_bf16 v[12:15], v[206:209], v[210:213], v[12:15]
	ds_bpermute_b32 v218, v248, v108
	ds_bpermute_b32 v219, v248, v109
	ds_bpermute_b32 v220, v248, v110
	ds_bpermute_b32 v221, v248, v111
	s_waitcnt lgkmcnt(0)
	v_mfma_f32_16x16x32_bf16 v[12:15], v[214:217], v[218:221], v[12:15]
	s_and_b32 s4, s9, -16
	s_andn2_b64 vcc, exec, s[0:1]
	v_add_u32_e32 v36, s8, v8
	s_barrier
	s_nop 7
	ds_write_b128 v11, v[12:15]
	ds_write_b32 v36, v195 offset:32768
	s_waitcnt lgkmcnt(0)
	s_barrier
	s_cbranch_vccnz .LBB0_1233
	s_ashr_i32 s5, s4, 31
	v_lshl_add_u64 v[12:13], s[4:5], 2, v[6:7]
	v_lshl_or_b32 v194, s11, 12, v10
	v_lshl_add_u64 v[28:29], v[12:13], 0, v[194:195]
	s_movk_i32 s4, 0x2000
	v_add_co_u32_e32 v30, vcc, s4, v28
	s_nop 1
	v_addc_co_u32_e32 v31, vcc, 0, v29, vcc
	v_add_co_u32_e32 v32, vcc, 0x3000, v28
	v_addc_co_u32_e32 v33, vcc, 0, v29, vcc
	ds_read_b128 v[12:15], v11
	ds_read_b128 v[16:19], v11 offset:2048
	ds_read_b128 v[20:23], v11 offset:4096
	ds_read_b128 v[24:27], v11 offset:6144
	s_waitcnt lgkmcnt(2)
	v_add_f32_e32 v12, v12, v16
	v_add_f32_e32 v13, v13, v17
	s_waitcnt lgkmcnt(0)
	v_add_f32_e32 v16, v20, v24
	v_add_f32_e32 v17, v21, v25
	v_add_f32_e32 v12, v12, v16
	v_add_f32_e32 v14, v14, v18
	v_add_f32_e32 v18, v22, v26
	v_add_f32_e32 v15, v15, v19
	v_add_f32_e32 v19, v23, v27
	v_add_f32_e32 v13, v13, v17
	v_add_f32_e32 v14, v14, v18
	v_add_f32_e32 v15, v15, v19
	s_waitcnt vmcnt(3)
	v_add_f32_e32 v12, v176, v12
	global_store_dword v[28:29], v12, off
	s_waitcnt vmcnt(3)
	v_add_f32_e32 v12, v13, v177
	s_waitcnt vmcnt(2)
	v_add_f32_e32 v13, v14, v178
	global_store_dword v[30:31], v12, off offset:-4096
	global_store_dword v[30:31], v13, off
	s_waitcnt vmcnt(3)
	v_add_f32_e32 v12, v15, v179
	global_store_dword v[32:33], v12, off
	s_branch .LBB0_1233
